# attention loop: score MFMA order M5 M7 M6 M8 on non-diagonal tiles so map-0 softmax starts earlier, two V reads under it, V fragments addressed from one base register with immediate offsets (6 fewer V
# speedup vs baseline: 1.0091x; 1.0091x over previous
; #define LAS __attribute__((address_space(3)))
; __device__ __forceinline__ void dattn_unit(LAS unsigned char* lds, int b, int h, int qb, const bf16* Q, const bf16* K, const bf16* V, bf16* YB, float lam, const float* subg, float oml, int tid) {
;     ...
;                     s0 = __builtin_amdgcn_mfma_f32_32x32x16_bf16(ka, qa, s0, 0, 0, 0);
;                     s1 = __builtin_amdgcn_mfma_f32_32x32x16_bf16(kb, qb, s1, 0, 0, 0);
;                     __builtin_amdgcn_sched_group_barrier(0x008, 2, 0);
;                     ka = ka2; kb = kb2; qa = qa2; qb = qb2; }
;             }
;             if (need_bm) { const LAS float* gb = tab + (159 - (q - (kvbase + 32 * sub + 4 * hi)));
; #pragma unroll
;                 for (int r = 0; r < 16; ++r) { const float bv = gb[(r & 3) + 8 * (r >> 2)]; s0[r] += bv; s1[r] += bv; } }
;     ...
;             for (int cb = 0; cb < 4; ++cb) { const LAS bf16* vp = Vt + (32 * cb + ql) * 72 + 32 * sub + 4 * hi;
;                 const v2u a0 = *(const LAS v2u*)(vp), a1 = *(const LAS v2u*)(vp + 8), a2 = *(const LAS v2u*)(vp + 16), a3 = *(const LAS v2u*)(vp + 24);
.Lqk_diag0:
	s_waitcnt lgkmcnt(4)
	v_mfma_f32_32x32x16_bf16 v[128:143], v[204:207], v[238:241], v[128:143]
	s_waitcnt lgkmcnt(1)
	v_mfma_f32_32x32x16_bf16 v[144:159], v[222:225], v[230:233], v[144:159]
	s_waitcnt lgkmcnt(0)
	v_mfma_f32_32x32x16_bf16 v[128:143], v[226:229], v[234:237], v[128:143]
	v_add_u32_e32 v200, s57, v198
	v_add_u32_e32 v212, 0x1227c, v200
	v_add_u32_e32 v214, 0x12284, v200
	v_add_u32_e32 v218, 0x1229c, v200
	v_add_u32_e32 v220, 0x122a4, v200
	v_add_u32_e32 v201, 0x122bc, v200
	v_add_u32_e32 v202, 0x122c4, v200
	v_add_u32_e32 v204, 0x122dc, v200
	v_add_u32_e32 v206, 0x122e4, v200
	ds_read2_b32 v[200:201], v201 offset1:1
	ds_read2_b32 v[202:203], v202 offset1:1
	ds_read2_b32 v[204:205], v204 offset1:1
	ds_read2_b32 v[206:207], v206 offset1:1
	ds_read2_b32 v[212:213], v212 offset1:1
	ds_read2_b32 v[214:215], v214 offset1:1
	ds_read2_b32 v[218:219], v218 offset1:1
	ds_read2_b32 v[220:221], v220 offset1:1
	s_waitcnt lgkmcnt(4)
	v_pk_add_f32 v[158:159], v[158:159], v[206:207]
	v_pk_add_f32 v[156:157], v[156:157], v[204:205]
	v_pk_add_f32 v[154:155], v[154:155], v[202:203]
	v_pk_add_f32 v[152:153], v[152:153], v[200:201]
	s_waitcnt lgkmcnt(0)
	v_pk_add_f32 v[150:151], v[150:151], v[220:221]
	v_pk_add_f32 v[148:149], v[148:149], v[218:219]
	v_pk_add_f32 v[146:147], v[146:147], v[214:215]
	v_pk_add_f32 v[144:145], v[144:145], v[212:213]
	v_pk_add_f32 v[142:143], v[142:143], v[206:207]
	v_pk_add_f32 v[140:141], v[140:141], v[204:205]
	v_pk_add_f32 v[138:139], v[138:139], v[202:203]
	v_pk_add_f32 v[136:137], v[136:137], v[200:201]
	v_pk_add_f32 v[134:135], v[134:135], v[220:221]
	v_pk_add_f32 v[132:133], v[132:133], v[218:219]
	v_pk_add_f32 v[130:131], v[130:131], v[214:215]
	v_pk_add_f32 v[128:129], v[128:129], v[212:213]
	v_add3_u32 v219, s38, v193, v192
	ds_read_b128 v[228:231], v219 offset:23040
	ds_read_b128 v[232:235], v219 offset:23072
	ds_read_b128 v[236:239], v219 offset:27648
	ds_read_b128 v[240:243], v219 offset:27680
	ds_read_b128 v[212:215], v219 offset:32256
	ds_read_b128 v[220:223], v219 offset:18432
	s_branch .Lsm0_0
.Lqk_diag1:
	s_waitcnt lgkmcnt(4)
	v_mfma_f32_32x32x16_bf16 v[128:143], v[218:221], v[212:215], v[128:143]
	s_waitcnt lgkmcnt(1)
	v_mfma_f32_32x32x16_bf16 v[144:159], v[226:229], v[234:237], v[144:159]
	s_waitcnt lgkmcnt(0)
	v_mfma_f32_32x32x16_bf16 v[128:143], v[230:233], v[238:241], v[128:143]
	v_add_u32_e32 v199, s57, v198
	v_add_u32_e32 v218, 0x122fc, v199
	v_add_u32_e32 v220, 0x12304, v199
	v_add_u32_e32 v222, 0x1231c, v199
	v_add_u32_e32 v224, 0x12324, v199
	v_add_u32_e32 v204, 0x1233c, v199
	v_add_u32_e32 v206, 0x12344, v199
	v_add_u32_e32 v212, 0x1235c, v199
	v_add_u32_e32 v199, 0x12364, v199
	ds_read2_b32 v[204:205], v204 offset1:1
	ds_read2_b32 v[206:207], v206 offset1:1
	ds_read2_b32 v[212:213], v212 offset1:1
	ds_read2_b32 v[214:215], v199 offset1:1
	ds_read2_b32 v[218:219], v218 offset1:1
	ds_read2_b32 v[220:221], v220 offset1:1
	ds_read2_b32 v[222:223], v222 offset1:1
	ds_read2_b32 v[224:225], v224 offset1:1
	s_waitcnt lgkmcnt(4)
	v_pk_add_f32 v[158:159], v[158:159], v[214:215]
	v_pk_add_f32 v[156:157], v[156:157], v[212:213]
	v_pk_add_f32 v[154:155], v[154:155], v[206:207]
	v_pk_add_f32 v[152:153], v[152:153], v[204:205]
	s_waitcnt lgkmcnt(0)
	v_pk_add_f32 v[150:151], v[150:151], v[224:225]
	v_pk_add_f32 v[148:149], v[148:149], v[222:223]
	v_pk_add_f32 v[146:147], v[146:147], v[220:221]
	v_pk_add_f32 v[144:145], v[144:145], v[218:219]
	v_pk_add_f32 v[142:143], v[142:143], v[214:215]
	v_pk_add_f32 v[140:141], v[140:141], v[212:213]
	v_pk_add_f32 v[138:139], v[138:139], v[206:207]
	v_pk_add_f32 v[136:137], v[136:137], v[204:205]
	v_pk_add_f32 v[134:135], v[134:135], v[224:225]
	v_pk_add_f32 v[132:133], v[132:133], v[222:223]
	v_pk_add_f32 v[130:131], v[130:131], v[220:221]
	v_pk_add_f32 v[128:129], v[128:129], v[218:219]
	v_add3_u32 v243, s38, v193, v192
	ds_read_b128 v[222:225], v243 offset:23104
	ds_read_b128 v[226:229], v243 offset:23136
	ds_read_b128 v[230:233], v243 offset:27712
	ds_read_b128 v[234:237], v243 offset:27744
	ds_read_b128 v[238:241], v243 offset:32320
	ds_read_b128 v[212:215], v243 offset:18496
	ds_read_b128 v[200:203], v243 offset:18528
	s_branch .Lsm0_1

; #define LAS __attribute__((address_space(3)))
; __device__ __forceinline__ void dattn_unit(LAS unsigned char* lds, int b, int h, int qb, const bf16* Q, const bf16* K, const bf16* V, bf16* YB, float lam, const float* subg, float oml, int tid) {
;     ...
;         if (t + 1 < NT) { const size_t adv = (size_t)(t + 1) * 64 * 1024; kr0 = *(const v4u*)(kg + adv); kr1 = *(const v4u*)(kg + adv + 64); vr0 = *(const v4u*)(vg + adv); vr1 = *(const v4u*)(vg + adv + 8); }
;         const LAS bf16* Ks = (const LAS bf16*)(lds + (t & 1) * AT_BUF + AT_KS); const LAS bf16* Vt = (const LAS bf16*)(lds + (t & 1) * AT_BUF + AT_VT);
;         const int kvbase = t * 64;
;         if (kvbase <= qmax) {
;     ...
; #pragma unroll
;         for (int sub = 0; sub < 2; ++sub) {
;             if (kvbase + 32 * sub > qmax) continue;
;             const bool need_bm = kvbase + 32 * sub + 31 + 113 > qmin;
;             LAS bf16x8* qsp = qs; asm volatile("" : "+v"(qsp));
;             f32x16 s0, s1;
; #pragma unroll
;             for (int r = 0; r < 16; ++r) { s0[r] = -mref[0]; s1[r] = -mref[1]; }
;             {
;                 const LAS bf16* kp = Ks + (32 * sub + ql) * 72 + hi * 8;
;                 bf16x8 ka = *(const LAS bf16x8*)kp, kb = *(const LAS bf16x8*)(kp + 64 * 72), qa = qsp[0], qb = qsp[4 * 64];
;                 __builtin_amdgcn_sched_group_barrier(0x100, 4, 0);
; #pragma unroll
;                 for (int ks = 0; ks < 4; ++ks) { bf16x8 ka2 = ka, kb2 = kb, qa2 = qa, qb2 = qb;
;                     if (ks < 3) { ka2 = *(const LAS bf16x8*)(kp + (ks + 1) * 16); kb2 = *(const LAS bf16x8*)(kp + 64 * 72 + (ks + 1) * 16); qa2 = qsp[(ks + 1) * 64]; qb2 = qsp[(4 + ks + 1) * 64];
;                         __builtin_amdgcn_sched_group_barrier(0x100, 4, 0); }
;                     s0 = __builtin_amdgcn_mfma_f32_32x32x16_bf16(ka, qa, s0, 0, 0, 0);
;                     s1 = __builtin_amdgcn_mfma_f32_32x32x16_bf16(kb, qb, s1, 0, 0, 0);
;                     __builtin_amdgcn_sched_group_barrier(0x008, 2, 0);
;                     ka = ka2; kb = kb2; qa = qa2; qb = qb2; }
;             }
.LBB0_227:
	v_lshl_add_u64 v[128:129], v[184:185], 0, s[16:17]
	s_mov_b32 s18, 0x1b020000
	v_add_co_u32_e32 v128, vcc, s18, v128
	v_lshl_add_u64 v[130:131], v[182:183], 0, s[16:17]
	s_nop 0
	v_addc_co_u32_e32 v129, vcc, 0, v129, vcc
	global_load_dwordx4 v[168:171], v[128:129], off
	global_load_dwordx4 v[172:175], v[128:129], off offset:128
	v_add_co_u32_e32 v128, vcc, 0xb020000, v130
	s_add_i32 s18, s58, 0xffffff50
	s_nop 0
	v_addc_co_u32_e32 v129, vcc, 0, v131, vcc
	global_load_dwordx4 v[164:167], v[128:129], off
	global_load_dwordx4 v[160:163], v[128:129], off offset:16
	s_cmp_gt_i32 s18, s35
	s_cbranch_scc1 .LBB0_226
	s_bitcmp1_b32 s59, 0
	s_cselect_b32 s18, 0x9000, 0
	s_add_i32 s38, s18, 0
	v_add_u32_e32 v136, s38, v208
	v_mov_b32_e32 v212, v189
	v_add_u32_e32 v199, v136, v192
	ds_read_b128 v[138:141], v199
	ds_read_b128 v[200:203], v199 offset:9216
	ds_read_b128 v[204:207], v212
	ds_read_b128 v[218:221], v212 offset:4096
	v_xor_b32_e32 v144, 0x80000000, v190
	v_xor_b32_e32 v128, 0x80000000, v191
	v_mov_b32_e32 v145, v144
	v_mov_b32_e32 v146, v144
	v_mov_b32_e32 v147, v144
	v_mov_b32_e32 v148, v144
	v_mov_b32_e32 v149, v144
	v_mov_b32_e32 v150, v144
	v_mov_b32_e32 v151, v144
	v_mov_b32_e32 v152, v144
	v_mov_b32_e32 v153, v144
	v_mov_b32_e32 v154, v144
	v_mov_b32_e32 v155, v144
	v_mov_b32_e32 v156, v144
	v_mov_b32_e32 v157, v144
	v_mov_b32_e32 v158, v144
	v_mov_b32_e32 v159, v144
	v_mov_b32_e32 v129, v128
	v_mov_b32_e32 v130, v128
	v_mov_b32_e32 v131, v128
	v_mov_b32_e32 v132, v128
	v_mov_b32_e32 v133, v128
	v_mov_b32_e32 v134, v128
	v_mov_b32_e32 v135, v128
	v_mov_b32_e32 v136, v128
	ds_read_b128 v[222:225], v199 offset:32
	ds_read_b128 v[226:229], v199 offset:9248
	ds_read_b128 v[230:233], v212 offset:1024
	ds_read_b128 v[234:237], v212 offset:5120
	s_waitcnt lgkmcnt(5)
	v_mfma_f32_32x32x16_bf16 v[144:159], v[138:141], v[204:207], v[144:159]
	v_mov_b32_e32 v137, v128
	v_mov_b32_e32 v138, v128
	v_mov_b32_e32 v139, v128
	v_mov_b32_e32 v140, v128
	v_mov_b32_e32 v141, v128
	v_mov_b32_e32 v142, v128
	v_mov_b32_e32 v143, v128
	s_sub_i32 s18, s58, 32
	s_cmp_le_i32 s18, s31
	s_waitcnt lgkmcnt(4)
	v_mfma_f32_32x32x16_bf16 v[128:143], v[200:203], v[218:221], v[128:143]
	ds_read_b128 v[200:203], v199 offset:64
	ds_read_b128 v[204:207], v199 offset:9280
	ds_read_b128 v[218:221], v212 offset:2048
	ds_read_b128 v[238:241], v212 offset:6144
	s_waitcnt lgkmcnt(5)
	v_mfma_f32_32x32x16_bf16 v[144:159], v[222:225], v[230:233], v[144:159]
	s_waitcnt lgkmcnt(4)
	v_mfma_f32_32x32x16_bf16 v[128:143], v[226:229], v[234:237], v[128:143]
	ds_read_b128 v[222:225], v199 offset:96
	ds_read_b128 v[226:229], v199 offset:9312
	ds_read_b128 v[230:233], v212 offset:3072
	ds_read_b128 v[234:237], v212 offset:7168
	s_waitcnt lgkmcnt(5)
	v_mfma_f32_32x32x16_bf16 v[144:159], v[200:203], v[218:221], v[144:159]
	s_cbranch_scc0 .Lqk_diag0
	s_waitcnt lgkmcnt(1)
	v_mfma_f32_32x32x16_bf16 v[144:159], v[222:225], v[230:233], v[144:159]
	v_add3_u32 v219, s38, v193, v192
	ds_read_b128 v[212:215], v219 offset:32256
	ds_read_b128 v[220:223], v219 offset:18432
	v_mfma_f32_32x32x16_bf16 v[128:143], v[204:207], v[238:241], v[128:143]
	s_waitcnt lgkmcnt(2)
	v_mfma_f32_32x32x16_bf16 v[128:143], v[226:229], v[234:237], v[128:143]
	ds_read_b128 v[228:231], v219 offset:23040
	ds_read_b128 v[232:235], v219 offset:23072
	ds_read_b128 v[236:239], v219 offset:27648
	ds_read_b128 v[240:243], v219 offset:27680
	s_nop 1
; #define LAS __attribute__((address_space(3)))
; __device__ __forceinline__ void dattn_unit(LAS unsigned char* lds, int b, int h, int qb, const bf16* Q, const bf16* K, const bf16* V, bf16* YB, float lam, const float* subg, float oml, int tid) {
;     ...
;             for (int cb = 0; cb < 4; ++cb) { const LAS bf16* vp = Vt + (32 * cb + ql) * 72 + 32 * sub + 4 * hi;
;                 const v2u a0 = *(const LAS v2u*)(vp), a1 = *(const LAS v2u*)(vp + 8), a2 = *(const LAS v2u*)(vp + 16), a3 = *(const LAS v2u*)(vp + 24);
;                 const v4u f0 = {a0.x, a0.y, a1.x, a1.y}, f1 = {a2.x, a2.y, a3.x, a3.y};
;                 o[0][cb] = __builtin_amdgcn_mfma_f32_32x32x16_bf16(__builtin_bit_cast(bf16x8, f0), pA0, o[0][cb], 0, 0, 0);
;                 o[1][cb] = __builtin_amdgcn_mfma_f32_32x32x16_bf16(__builtin_bit_cast(bf16x8, f0), pA1, o[1][cb], 0, 0, 0);
;                 o[0][cb] = __builtin_amdgcn_mfma_f32_32x32x16_bf16(__builtin_bit_cast(bf16x8, f1), pB0, o[0][cb], 0, 0, 0);
;                 o[1][cb] = __builtin_amdgcn_mfma_f32_32x32x16_bf16(__builtin_bit_cast(bf16x8, f1), pB1, o[1][cb], 0, 0, 0); }
.Lsm0_0:
	v_exp_f32_e32 v201, v144
	v_exp_f32_e32 v202, v145
	v_exp_f32_e32 v203, v146
	v_exp_f32_e32 v204, v147
	v_add_f32_e32 v144, 0, v201
	v_exp_f32_e32 v205, v148
	v_add_f32_e32 v144, v202, v144
	v_exp_f32_e32 v206, v149
	v_add_f32_e32 v144, v203, v144
	v_exp_f32_e32 v207, v150
	v_add_f32_e32 v144, v204, v144
	v_exp_f32_e32 v218, v151
	v_add_f32_e32 v144, v205, v144
	v_exp_f32_e32 v147, v152
	v_add_f32_e32 v144, v206, v144
	v_exp_f32_e32 v148, v153
	v_add_f32_e32 v144, v207, v144
	v_exp_f32_e32 v149, v154
	v_add_f32_e32 v144, v218, v144
	v_exp_f32_e32 v150, v155
	v_add_f32_e32 v144, v147, v144
	v_exp_f32_e32 v151, v156
	v_add_f32_e32 v144, v148, v144
	v_exp_f32_e32 v152, v157
	v_add_f32_e32 v144, v149, v144
	v_exp_f32_e32 v153, v158
	v_add_f32_e32 v144, v150, v144
	v_exp_f32_e32 v154, v159
	v_add_f32_e32 v144, v151, v144
	v_add_f32_e32 v144, v152, v144
	v_add_f32_e32 v144, v153, v144
	v_add_f32_e32 v145, v154, v144
	v_cmp_lt_f32_e32 vcc, s82, v145
	s_cmp_lg_u64 vcc, 0
	v_mov_b32_e32 v144, 1.0
	s_cselect_b64 s[48:49], -1, 0
	v_mov_b32_e32 v146, 1.0
	s_cbranch_vccz .LBB0_232
	v_max_f32_e32 v146, v204, v204
	v_max_f32_e32 v155, v203, v203
	v_max_f32_e32 v146, v155, v146
	v_max_f32_e32 v155, v218, v218
	v_max_f32_e32 v156, v207, v207
	v_max_f32_e32 v155, v156, v155
	v_max_f32_e32 v156, v148, v148
	v_max_f32_e32 v157, v147, v147
	v_max_f32_e32 v156, v157, v156
	v_max_f32_e32 v157, v150, v150
	v_max_f32_e32 v158, v149, v149
	v_max_f32_e32 v157, v158, v157
	v_max_f32_e32 v158, v154, v154
	v_max_f32_e32 v159, v153, v153
	v_max_f32_e32 v158, v159, v158
	v_max3_f32 v158, v151, v152, v158
	v_max3_f32 v146, v201, v202, v146
	v_max3_f32 v155, v205, v206, v155
	v_max3_f32 v156, v156, v157, v158
	v_max3_f32 v146, v146, v155, v156
	v_mov_b32_e32 v155, v146
	s_nop 1
	v_permlane32_swap_b32_e32 v146, v155
	v_max_f32_e32 v155, v155, v155
	v_max_f32_e32 v146, v146, v146
	v_max_f32_e32 v146, v146, v155
.LBB0_232:
	v_cvt_pk_bf16_f32 v224, v201, v202
	v_cvt_pk_bf16_f32 v225, v203, v204
	v_cvt_pk_bf16_f32 v226, v205, v206
	v_cvt_pk_bf16_f32 v227, v207, v218
	v_cvt_pk_bf16_f32 v148, v147, v148
	v_cvt_pk_bf16_f32 v149, v149, v150
	v_cvt_pk_bf16_f32 v150, v151, v152
	v_cvt_pk_bf16_f32 v151, v153, v154
	ds_read_b128 v[204:207], v219 offset:18464
	ds_read_b128 v[200:203], v219 offset:32288
	v_add_f32_e32 v179, v179, v145
	v_exp_f32_e32 v155, v128
	v_exp_f32_e32 v129, v129
	v_exp_f32_e32 v130, v130
	v_exp_f32_e32 v131, v131
	s_waitcnt lgkmcnt(2)
	v_mfma_f32_32x32x16_bf16 v[80:95], v[228:231], v[224:227], v[80:95]
	v_add_f32_e32 v128, 0, v155
	v_exp_f32_e32 v132, v132
	v_add_f32_e32 v128, v129, v128
	v_exp_f32_e32 v156, v133
	v_mfma_f32_32x32x16_bf16 v[80:95], v[232:235], v[148:151], v[80:95]
	v_add_f32_e32 v128, v130, v128
	v_exp_f32_e32 v157, v134
	v_add_f32_e32 v128, v131, v128
	v_exp_f32_e32 v158, v135
	v_mfma_f32_32x32x16_bf16 v[48:63], v[236:239], v[224:227], v[48:63]
	v_add_f32_e32 v128, v132, v128
	v_exp_f32_e32 v133, v136
	v_add_f32_e32 v128, v156, v128
	v_exp_f32_e32 v134, v137
	v_mfma_f32_32x32x16_bf16 v[48:63], v[240:243], v[148:151], v[48:63]
	v_add_f32_e32 v128, v157, v128
	v_exp_f32_e32 v135, v138
	v_add_f32_e32 v128, v158, v128
	v_exp_f32_e32 v136, v139
	v_mfma_f32_32x32x16_bf16 v[16:31], v[212:215], v[224:227], v[16:31]
	v_add_f32_e32 v128, v133, v128
	v_exp_f32_e32 v137, v140
	v_add_f32_e32 v128, v134, v128
	v_exp_f32_e32 v138, v141
	v_mfma_f32_32x32x16_bf16 v[112:127], v[220:223], v[224:227], v[112:127]
	v_add_f32_e32 v128, v135, v128
	v_exp_f32_e32 v139, v142
	v_add_f32_e32 v128, v136, v128
	v_exp_f32_e32 v140, v143
	s_waitcnt lgkmcnt(1)
	v_mfma_f32_32x32x16_bf16 v[112:127], v[204:207], v[148:151], v[112:127]
	v_add_f32_e32 v128, v137, v128
	v_add_f32_e32 v128, v138, v128
	v_add_f32_e32 v128, v139, v128
	v_add_f32_e32 v128, v140, v128
	s_waitcnt lgkmcnt(0)
	v_mfma_f32_32x32x16_bf16 v[16:31], v[200:203], v[148:151], v[16:31]
	v_cmp_lt_f32_e32 vcc, s82, v128
	s_cmp_lg_u64 vcc, 0
	s_cselect_b64 s[46:47], -1, 0
	s_cbranch_vccz .LBB0_234
	v_max_f32_e32 v141, v131, v131
	v_max_f32_e32 v142, v130, v130
	v_max_f32_e32 v141, v142, v141
	v_max_f32_e32 v142, v158, v158
	v_max_f32_e32 v143, v157, v157
	v_max_f32_e32 v142, v143, v142
	v_max_f32_e32 v143, v134, v134
	v_max_f32_e32 v144, v133, v133
	v_max_f32_e32 v143, v144, v143
	v_max_f32_e32 v144, v136, v136
	v_max_f32_e32 v159, v135, v135
	v_max_f32_e32 v144, v159, v144
	v_max_f32_e32 v159, v140, v140
	v_max_f32_e32 v147, v139, v139
	v_max_f32_e32 v159, v147, v159
	v_max3_f32 v159, v137, v138, v159
	v_max3_f32 v141, v155, v129, v141
	v_max3_f32 v142, v132, v156, v142
	v_max3_f32 v143, v143, v144, v159
	v_max3_f32 v141, v141, v142, v143
	v_mov_b32_e32 v142, v141
	s_nop 1
	v_permlane32_swap_b32_e32 v141, v142
	v_max_f32_e32 v142, v142, v142
	v_max_f32_e32 v141, v141, v141
	v_max_f32_e32 v144, v141, v142

; #define LAS __attribute__((address_space(3)))
; __device__ __forceinline__ void dattn_unit(LAS unsigned char* lds, int b, int h, int qb, const bf16* Q, const bf16* K, const bf16* V, bf16* YB, float lam, const float* subg, float oml, int tid) {
;     ...
; #pragma unroll
;         for (int sub = 0; sub < 2; ++sub) {
;             if (kvbase + 32 * sub > qmax) continue;
;             const bool need_bm = kvbase + 32 * sub + 31 + 113 > qmin;
;             LAS bf16x8* qsp = qs; asm volatile("" : "+v"(qsp));
;             f32x16 s0, s1;
; #pragma unroll
;             for (int r = 0; r < 16; ++r) { s0[r] = -mref[0]; s1[r] = -mref[1]; }
;             {
;                 const LAS bf16* kp = Ks + (32 * sub + ql) * 72 + hi * 8;
;                 bf16x8 ka = *(const LAS bf16x8*)kp, kb = *(const LAS bf16x8*)(kp + 64 * 72), qa = qsp[0], qb = qsp[4 * 64];
;                 __builtin_amdgcn_sched_group_barrier(0x100, 4, 0);
; #pragma unroll
;                 for (int ks = 0; ks < 4; ++ks) { bf16x8 ka2 = ka, kb2 = kb, qa2 = qa, qb2 = qb;
;                     if (ks < 3) { ka2 = *(const LAS bf16x8*)(kp + (ks + 1) * 16); kb2 = *(const LAS bf16x8*)(kp + 64 * 72 + (ks + 1) * 16); qa2 = qsp[(ks + 1) * 64]; qb2 = qsp[(4 + ks + 1) * 64];
;                         __builtin_amdgcn_sched_group_barrier(0x100, 4, 0); }
;                     s0 = __builtin_amdgcn_mfma_f32_32x32x16_bf16(ka, qa, s0, 0, 0, 0);
;                     s1 = __builtin_amdgcn_mfma_f32_32x32x16_bf16(kb, qb, s1, 0, 0, 0);
;                     __builtin_amdgcn_sched_group_barrier(0x008, 2, 0);
;                     ka = ka2; kb = kb2; qa = qa2; qb = qb2; }
;             }
.LBB0_238:
	s_add_i32 s18, s58, 0xffffff70
	s_cmp_gt_i32 s18, s35
	s_cbranch_scc1 .LBB0_226
	v_mov_b32_e32 v242, v189
	ds_read_b128 v[138:141], v199 offset:4608
	ds_read_b128 v[204:207], v199 offset:13824
	ds_read_b128 v[218:221], v242
	ds_read_b128 v[222:225], v242 offset:4096
	v_xor_b32_e32 v144, 0x80000000, v190
	v_xor_b32_e32 v128, 0x80000000, v191
	v_mov_b32_e32 v145, v144
	v_mov_b32_e32 v146, v144
	v_mov_b32_e32 v147, v144
	v_mov_b32_e32 v148, v144
	v_mov_b32_e32 v149, v144
	v_mov_b32_e32 v150, v144
	v_mov_b32_e32 v151, v144
	v_mov_b32_e32 v152, v144
	v_mov_b32_e32 v153, v144
	v_mov_b32_e32 v154, v144
	v_mov_b32_e32 v155, v144
	v_mov_b32_e32 v156, v144
	v_mov_b32_e32 v157, v144
	v_mov_b32_e32 v158, v144
	v_mov_b32_e32 v159, v144
	v_mov_b32_e32 v129, v128
	v_mov_b32_e32 v130, v128
	v_mov_b32_e32 v131, v128
	v_mov_b32_e32 v132, v128
	v_mov_b32_e32 v133, v128
	v_mov_b32_e32 v134, v128
	v_mov_b32_e32 v135, v128
	v_mov_b32_e32 v136, v128
	ds_read_b128 v[226:229], v199 offset:4640
	ds_read_b128 v[230:233], v199 offset:13856
	ds_read_b128 v[234:237], v242 offset:1024
	ds_read_b128 v[238:241], v242 offset:5120
	s_waitcnt lgkmcnt(5)
	v_mfma_f32_32x32x16_bf16 v[144:159], v[138:141], v[218:221], v[144:159]
	v_mov_b32_e32 v137, v128
	v_mov_b32_e32 v138, v128
	v_mov_b32_e32 v139, v128
	v_mov_b32_e32 v140, v128
	v_mov_b32_e32 v141, v128
	v_mov_b32_e32 v142, v128
	v_mov_b32_e32 v143, v128
	s_cmp_le_i32 s58, s31
	s_waitcnt lgkmcnt(4)
	v_mfma_f32_32x32x16_bf16 v[128:143], v[204:207], v[222:225], v[128:143]
	ds_read_b128 v[204:207], v199 offset:4672
	ds_read_b128 v[218:221], v199 offset:13888
	ds_read_b128 v[222:225], v242 offset:2048
	ds_read_b128 v[212:215], v242 offset:6144
	s_waitcnt lgkmcnt(5)
	v_mfma_f32_32x32x16_bf16 v[144:159], v[226:229], v[234:237], v[144:159]
	s_waitcnt lgkmcnt(4)
	v_mfma_f32_32x32x16_bf16 v[128:143], v[230:233], v[238:241], v[128:143]
	ds_read_b128 v[226:229], v199 offset:4704
	ds_read_b128 v[230:233], v199 offset:13920
	ds_read_b128 v[234:237], v242 offset:3072
	ds_read_b128 v[238:241], v242 offset:7168
	s_waitcnt lgkmcnt(5)
	v_mfma_f32_32x32x16_bf16 v[144:159], v[204:207], v[222:225], v[144:159]
	s_cbranch_scc0 .Lqk_diag1
	s_waitcnt lgkmcnt(1)
	v_mfma_f32_32x32x16_bf16 v[144:159], v[226:229], v[234:237], v[144:159]
	v_add3_u32 v243, s38, v193, v192
	ds_read_b128 v[222:225], v243 offset:23104
	ds_read_b128 v[226:229], v243 offset:23136
	v_mfma_f32_32x32x16_bf16 v[128:143], v[218:221], v[212:215], v[128:143]
	s_waitcnt lgkmcnt(2)
	v_mfma_f32_32x32x16_bf16 v[128:143], v[230:233], v[238:241], v[128:143]
	ds_read_b128 v[230:233], v243 offset:27712
	ds_read_b128 v[234:237], v243 offset:27744
	ds_read_b128 v[238:241], v243 offset:32320
	ds_read_b128 v[212:215], v243 offset:18496
	ds_read_b128 v[200:203], v243 offset:18528
	s_nop 1
.Lsm0_1:
	v_exp_f32_e32 v199, v144
	v_exp_f32_e32 v204, v145
	v_exp_f32_e32 v205, v146
	v_exp_f32_e32 v206, v147
	v_add_f32_e32 v144, 0, v199
	v_exp_f32_e32 v207, v148
	v_add_f32_e32 v144, v204, v144
	v_exp_f32_e32 v218, v149
	v_add_f32_e32 v144, v205, v144
	v_exp_f32_e32 v219, v150
	v_add_f32_e32 v144, v206, v144
	v_exp_f32_e32 v220, v151
	v_add_f32_e32 v144, v207, v144
	v_exp_f32_e32 v147, v152
	v_add_f32_e32 v144, v218, v144
	v_exp_f32_e32 v148, v153
	v_add_f32_e32 v144, v219, v144
	v_exp_f32_e32 v149, v154
	v_add_f32_e32 v144, v220, v144
	v_exp_f32_e32 v150, v155
	v_add_f32_e32 v144, v147, v144
	v_exp_f32_e32 v151, v156
	v_add_f32_e32 v144, v148, v144
	v_exp_f32_e32 v152, v157
	v_add_f32_e32 v144, v149, v144
	v_exp_f32_e32 v153, v158
	v_add_f32_e32 v144, v150, v144
	v_exp_f32_e32 v154, v159
	v_add_f32_e32 v144, v151, v144
	v_add_f32_e32 v144, v152, v144
	v_add_f32_e32 v144, v153, v144
	v_add_f32_e32 v145, v154, v144
	v_cmp_lt_f32_e32 vcc, s82, v145
	s_cmp_lg_u64 vcc, 0
	v_mov_b32_e32 v144, 1.0
	s_cselect_b64 s[48:49], -1, 0
	v_mov_b32_e32 v146, 1.0
	s_cbranch_vccz .LBB0_243
	v_max_f32_e32 v146, v206, v206
	v_max_f32_e32 v155, v205, v205
	v_max_f32_e32 v146, v155, v146
	v_max_f32_e32 v155, v220, v220
	v_max_f32_e32 v156, v219, v219
	v_max_f32_e32 v155, v156, v155
	v_max_f32_e32 v156, v148, v148
	v_max_f32_e32 v157, v147, v147
	v_max_f32_e32 v156, v157, v156
	v_max_f32_e32 v157, v150, v150
	v_max_f32_e32 v158, v149, v149
	v_max_f32_e32 v157, v158, v157
	v_max_f32_e32 v158, v154, v154
	v_max_f32_e32 v159, v153, v153
	v_max_f32_e32 v158, v159, v158
	v_max3_f32 v158, v151, v152, v158
	v_max3_f32 v146, v199, v204, v146
	v_max3_f32 v155, v207, v218, v155
	v_max3_f32 v156, v156, v157, v158
	v_max3_f32 v146, v146, v155, v156
	v_mov_b32_e32 v155, v146
	s_nop 1
	v_permlane32_swap_b32_e32 v146, v155
	v_max_f32_e32 v155, v155, v155
	v_max_f32_e32 v146, v146, v146
	v_max_f32_e32 v146, v146, v155
; __device__ __forceinline__ void dattn_unit(LAS unsigned char* lds, int b, int h, int qb, const bf16* Q, const bf16* K, const bf16* V, bf16* YB, float lam, const float* subg, float oml, int tid) {
;     ...
; #pragma unroll
;         for (int sub = 0; sub < 2; ++sub) {
;             if (kvbase + 32 * sub > qmax) continue;
;             const bool need_bm = kvbase + 32 * sub + 31 + 113 > qmin;
;             LAS bf16x8* qsp = qs; asm volatile("" : "+v"(qsp));
;             f32x16 s0, s1;
; #pragma unroll
;             for (int r = 0; r < 16; ++r) { s0[r] = -mref[0]; s1[r] = -mref[1]; }
;             {
;                 const LAS bf16* kp = Ks + (32 * sub + ql) * 72 + hi * 8;
;                 bf16x8 ka = *(const LAS bf16x8*)kp, kb = *(const LAS bf16x8*)(kp + 64 * 72), qa = qsp[0], qb = qsp[4 * 64];
;                 __builtin_amdgcn_sched_group_barrier(0x100, 4, 0);
; #pragma unroll
;                 for (int ks = 0; ks < 4; ++ks) { bf16x8 ka2 = ka, kb2 = kb, qa2 = qa, qb2 = qb;
;                     if (ks < 3) { ka2 = *(const LAS bf16x8*)(kp + (ks + 1) * 16); kb2 = *(const LAS bf16x8*)(kp + 64 * 72 + (ks + 1) * 16); qa2 = qsp[(ks + 1) * 64]; qb2 = qsp[(4 + ks + 1) * 64];
;                         __builtin_amdgcn_sched_group_barrier(0x100, 4, 0); }
;                     s0 = __builtin_amdgcn_mfma_f32_32x32x16_bf16(ka, qa, s0, 0, 0, 0);
;                     s1 = __builtin_amdgcn_mfma_f32_32x32x16_bf16(kb, qb, s1, 0, 0, 0);
;                     __builtin_amdgcn_sched_group_barrier(0x008, 2, 0);
;                     ka = ka2; kb = kb2; qa = qa2; qb = qb2; }
;             }
;             if (need_bm) { const LAS float* gb = tab + (159 - (q - (kvbase + 32 * sub + 4 * hi)));
; #pragma unroll
;                 for (int r = 0; r < 16; ++r) { const float bv = gb[(r & 3) + 8 * (r >> 2)]; s0[r] += bv; s1[r] += bv; } }
;             bf16x8 pA0, pB0, pA1, pB1; bool trig[2]; float pmx[2] = {1.f, 1.f};
;             AT_SOFTMAX(s0, 0, pA0, pB0);
;             AT_SOFTMAX(s1, 1, pA1, pB1);
; #pragma unroll
;             for (int cb = 0; cb < 4; ++cb) { const LAS bf16* vp = Vt + (32 * cb + ql) * 72 + 32 * sub + 4 * hi;
;                 const v2u a0 = *(const LAS v2u*)(vp), a1 = *(const LAS v2u*)(vp + 8), a2 = *(const LAS v2u*)(vp + 16), a3 = *(const LAS v2u*)(vp + 24);
;                 const v4u f0 = {a0.x, a0.y, a1.x, a1.y}, f1 = {a2.x, a2.y, a3.x, a3.y};
.LBB0_243:
	v_cvt_pk_bf16_f32 v205, v205, v206
	v_cvt_pk_bf16_f32 v206, v207, v218
	v_cvt_pk_bf16_f32 v207, v219, v220
	v_cvt_pk_bf16_f32 v204, v199, v204
	v_cvt_pk_bf16_f32 v148, v147, v148
	v_cvt_pk_bf16_f32 v149, v149, v150
	v_cvt_pk_bf16_f32 v150, v151, v152
	v_cvt_pk_bf16_f32 v151, v153, v154
	ds_read_b128 v[218:221], v243 offset:32352
	v_add_f32_e32 v179, v179, v145
	v_exp_f32_e32 v155, v128
	v_exp_f32_e32 v129, v129
	v_exp_f32_e32 v130, v130
	v_exp_f32_e32 v131, v131
	s_waitcnt lgkmcnt(1)
	v_mfma_f32_32x32x16_bf16 v[80:95], v[222:225], v[204:207], v[80:95]
	v_add_f32_e32 v128, 0, v155
	v_exp_f32_e32 v132, v132
	v_add_f32_e32 v128, v129, v128
	v_exp_f32_e32 v156, v133
	v_mfma_f32_32x32x16_bf16 v[80:95], v[226:229], v[148:151], v[80:95]
	v_add_f32_e32 v128, v130, v128
	v_exp_f32_e32 v157, v134
	v_add_f32_e32 v128, v131, v128
	v_exp_f32_e32 v158, v135
	v_mfma_f32_32x32x16_bf16 v[48:63], v[230:233], v[204:207], v[48:63]
	v_add_f32_e32 v128, v132, v128
	v_exp_f32_e32 v133, v136
	v_add_f32_e32 v128, v156, v128
	v_exp_f32_e32 v134, v137
	v_mfma_f32_32x32x16_bf16 v[48:63], v[234:237], v[148:151], v[48:63]
	v_add_f32_e32 v128, v157, v128
	v_exp_f32_e32 v135, v138
	v_add_f32_e32 v128, v158, v128
	v_exp_f32_e32 v136, v139
	v_mfma_f32_32x32x16_bf16 v[16:31], v[238:241], v[204:207], v[16:31]
	v_add_f32_e32 v128, v133, v128
	v_exp_f32_e32 v137, v140
	v_add_f32_e32 v128, v134, v128
	v_exp_f32_e32 v138, v141
	v_mfma_f32_32x32x16_bf16 v[112:127], v[212:215], v[204:207], v[112:127]
	v_add_f32_e32 v128, v135, v128
	v_exp_f32_e32 v139, v142
	v_add_f32_e32 v128, v136, v128
	v_exp_f32_e32 v140, v143
	v_mfma_f32_32x32x16_bf16 v[112:127], v[200:203], v[148:151], v[112:127]
	v_add_f32_e32 v128, v137, v128
	v_add_f32_e32 v128, v138, v128
	v_add_f32_e32 v128, v139, v128
	v_add_f32_e32 v128, v140, v128
	s_waitcnt lgkmcnt(0)
	v_mfma_f32_32x32x16_bf16 v[16:31], v[218:221], v[148:151], v[16:31]
	v_cmp_lt_f32_e32 vcc, s82, v128
	s_cmp_lg_u64 vcc, 0
	s_cselect_b64 s[46:47], -1, 0
	s_cbranch_vccz .LBB0_245
	v_max_f32_e32 v141, v131, v131
	v_max_f32_e32 v142, v130, v130
	v_max_f32_e32 v141, v142, v141
	v_max_f32_e32 v142, v158, v158
	v_max_f32_e32 v143, v157, v157
	v_max_f32_e32 v142, v143, v142
	v_max_f32_e32 v143, v134, v134
	v_max_f32_e32 v144, v133, v133
	v_max_f32_e32 v143, v144, v143
	v_max_f32_e32 v144, v136, v136
	v_max_f32_e32 v159, v135, v135
	v_max_f32_e32 v144, v159, v144
	v_max_f32_e32 v159, v140, v140
	v_max_f32_e32 v147, v139, v139
	v_max_f32_e32 v159, v147, v159
	v_max3_f32 v159, v137, v138, v159
	v_max3_f32 v141, v155, v129, v141
	v_max3_f32 v142, v132, v156, v142
	v_max3_f32 v143, v143, v144, v159
	v_max3_f32 v141, v141, v142, v143
	v_mov_b32_e32 v142, v141
	s_nop 1
	v_permlane32_swap_b32_e32 v141, v142
	v_max_f32_e32 v142, v142, v142
	v_max_f32_e32 v141, v141, v141
	v_max_f32_e32 v144, v141, v142
